# hand-written selected-attention block loop: masked-Q single-accumulator QK, folded bias/scale FMA, lazy row-sum, SGPR-base loads, 1-block K prefetch
# speedup vs baseline: 1.0302x; 1.0302x over previous
.LBB0_1550:
	s_or_b32 s70, s23, s97
	s_ashr_i32 s5, s70, 31
	v_readlane_b32 s30, v243, 32
	v_and_b32_e32 v76, 15, v181
	s_add_u32 s27, s70, s30
	s_addc_u32 s29, s5, 0
	s_mul_i32 s5, s29, 0x1800
	v_mad_u64_u32 v[44:45], s[30:31], s27, v212, v[68:69]
	v_lshl_add_u32 v76, v76, 2, s25
	v_add_u32_e32 v45, s5, v45
	global_load_dwordx4 v[36:39], v[44:45], off
	global_load_dwordx4 v[40:43], v[44:45], off offset:64
	ds_read_b32 v76, v76
	s_lshl_b32 s5, s23, 2
	s_add_i32 s5, s96, s5
	v_mov_b32_e32 v77, s5
	ds_read_b32 v77, v77 offset:17408
	v_lshlrev_b32_e32 v252, 4, v181
	v_readfirstlane_b32 s46, v70
	v_readfirstlane_b32 s47, v71
	v_readfirstlane_b32 s62, v72
	v_readfirstlane_b32 s63, v73
	v_mov_b64_e32 v[20:21], 0
	v_mov_b64_e32 v[22:23], 0
	v_mov_b64_e32 v[24:25], 0
	v_mov_b64_e32 v[26:27], 0
	v_mov_b64_e32 v[28:29], 0
	v_mov_b64_e32 v[30:31], 0
	v_mov_b64_e32 v[32:33], 0
	v_mov_b64_e32 v[34:35], 0
	v_sub_u32_e32 v104, s70, v82
	v_mov_b32_e32 v78, 0
	v_mov_b32_e32 v245, 0xff800000
	s_waitcnt lgkmcnt(0)
	v_mul_f32_e32 v253, 0x3fb8aa3b, v81
	v_readfirstlane_b32 s35, v77
	v_readlane_b32 s54, v76, 0
	v_mov_b32_e32 v77, 0
	v_mov_b32_e32 v79, v253
	s_mov_b32 s48, 0
	s_lshl_b32 s51, s54, 12
	s_add_u32 s30, s46, s51
	s_addc_u32 s31, s47, 0
	global_load_dwordx4 v[2:5], v252, s[30:31]
	global_load_dwordx4 v[6:9], v252, s[30:31] offset:1024
	global_load_dwordx4 v[12:15], v252, s[30:31] offset:2048
	global_load_dwordx4 v[16:19], v252, s[30:31] offset:3072
	s_add_u32 s30, s62, s51
	s_addc_u32 s31, s63, 0
	global_load_dwordx4 v[52:55], v252, s[30:31]
	global_load_dwordx4 v[56:59], v252, s[30:31] offset:1024
	global_load_dwordx4 v[60:63], v252, s[30:31] offset:2048
	global_load_dwordx4 v[64:67], v252, s[30:31] offset:3072
	s_and_b64 s[4:5], s[12:13], s[14:15]
	s_andn2_b64 s[50:51], s[14:15], s[12:13]
	s_andn2_b64 s[70:71], s[12:13], s[14:15]
	s_nor_b64 s[76:77], s[12:13], s[14:15]
	s_waitcnt vmcnt(8)
	v_lshlrev_b32_e32 v254, 16, v36
	v_and_b32_e32 v255, 0xffff0000, v36
	v_mul_f32_e32 v254, 0x41000000, v254
	v_mul_f32_e32 v255, 0x41000000, v255
	v_lshlrev_b32_e32 v250, 16, v37
	v_and_b32_e32 v251, 0xffff0000, v37
	v_cvt_pk_fp8_f32 v100, v254, v255
	v_mul_f32_e32 v250, 0x41000000, v250
	v_mul_f32_e32 v251, 0x41000000, v251
	s_nop 0
	v_cvt_pk_fp8_f32 v100, v250, v251 op_sel:[0,0,1]
	v_lshlrev_b32_e32 v254, 16, v38
	v_and_b32_e32 v255, 0xffff0000, v38
	v_mul_f32_e32 v254, 0x41000000, v254
	v_mul_f32_e32 v255, 0x41000000, v255
	v_lshlrev_b32_e32 v250, 16, v39
	v_and_b32_e32 v251, 0xffff0000, v39
	v_cvt_pk_fp8_f32 v101, v254, v255
	v_mul_f32_e32 v250, 0x41000000, v250
	v_mul_f32_e32 v251, 0x41000000, v251
	s_nop 0
	v_cvt_pk_fp8_f32 v101, v250, v251 op_sel:[0,0,1]
	v_lshlrev_b32_e32 v254, 16, v40
	v_and_b32_e32 v255, 0xffff0000, v40
	v_mul_f32_e32 v254, 0x41000000, v254
	v_mul_f32_e32 v255, 0x41000000, v255
	v_lshlrev_b32_e32 v250, 16, v41
	v_and_b32_e32 v251, 0xffff0000, v41
	v_cvt_pk_fp8_f32 v102, v254, v255
	v_mul_f32_e32 v250, 0x41000000, v250
	v_mul_f32_e32 v251, 0x41000000, v251
	s_nop 0
	v_cvt_pk_fp8_f32 v102, v250, v251 op_sel:[0,0,1]
	v_lshlrev_b32_e32 v254, 16, v42
	v_and_b32_e32 v255, 0xffff0000, v42
	v_mul_f32_e32 v254, 0x41000000, v254
	v_mul_f32_e32 v255, 0x41000000, v255
	v_lshlrev_b32_e32 v250, 16, v43
	v_and_b32_e32 v251, 0xffff0000, v43
	v_cvt_pk_fp8_f32 v103, v254, v255
	v_mul_f32_e32 v250, 0x41000000, v250
	v_mul_f32_e32 v251, 0x41000000, v251
	s_nop 0
	v_cvt_pk_fp8_f32 v103, v250, v251 op_sel:[0,0,1]
	s_nop 1
	v_cndmask_b32_e64 v84, 0, v100, s[4:5]
	v_cndmask_b32_e64 v85, 0, v101, s[4:5]
	v_cndmask_b32_e64 v86, 0, v102, s[4:5]
	v_cndmask_b32_e64 v87, 0, v103, s[4:5]
	v_cndmask_b32_e64 v88, 0, v100, s[50:51]
	v_cndmask_b32_e64 v89, 0, v101, s[50:51]
	v_cndmask_b32_e64 v90, 0, v102, s[50:51]
	v_cndmask_b32_e64 v91, 0, v103, s[50:51]
	v_cndmask_b32_e64 v92, 0, v100, s[70:71]
	v_cndmask_b32_e64 v93, 0, v101, s[70:71]
	v_cndmask_b32_e64 v94, 0, v102, s[70:71]
	v_cndmask_b32_e64 v95, 0, v103, s[70:71]
	v_cndmask_b32_e64 v96, 0, v100, s[76:77]
	v_cndmask_b32_e64 v97, 0, v101, s[76:77]
	v_cndmask_b32_e64 v98, 0, v102, s[76:77]
	v_cndmask_b32_e64 v99, 0, v103, s[76:77]
	s_nop 1
.Lsel2_A:
	s_waitcnt vmcnt(4)
	v_mfma_f32_16x16x32_fp8_fp8 v[100:103], v[2:3], v[84:85], 0
	v_mfma_f32_16x16x32_fp8_fp8 v[100:103], v[4:5], v[86:87], v[100:103]
	v_mfma_f32_16x16x32_fp8_fp8 v[100:103], v[6:7], v[88:89], v[100:103]
	v_mfma_f32_16x16x32_fp8_fp8 v[100:103], v[8:9], v[90:91], v[100:103]
	v_mfma_f32_16x16x32_fp8_fp8 v[100:103], v[12:13], v[92:93], v[100:103]
	v_mfma_f32_16x16x32_fp8_fp8 v[100:103], v[14:15], v[94:95], v[100:103]
	v_mfma_f32_16x16x32_fp8_fp8 v[100:103], v[16:17], v[96:97], v[100:103]
	v_mfma_f32_16x16x32_fp8_fp8 v[100:103], v[18:19], v[98:99], v[100:103]
	s_add_i32 s5, s48, 1
	s_cmp_lt_i32 s5, s35
	s_cbranch_scc0 .Lsel2_A_nonext
	v_readlane_b32 s50, v76, s5
	s_lshl_b32 s51, s50, 12
	s_add_u32 s30, s46, s51
	s_addc_u32 s31, s47, 0
	global_load_dwordx4 v[36:39], v252, s[30:31]
	global_load_dwordx4 v[40:43], v252, s[30:31] offset:1024
	global_load_dwordx4 v[44:47], v252, s[30:31] offset:2048
	global_load_dwordx4 v[48:51], v252, s[30:31] offset:3072
	s_branch .Lsel2_A_sm
.Lsel2_A_nonext:
	s_nop 6
.Lsel2_A_sm:
	s_cmp_ge_i32 s54, s21
	s_cbranch_scc1 .Lsel2_A_near
	v_fmamk_f32 v100, v100, 0x3e38aa3b, v79
	v_fmamk_f32 v101, v101, 0x3e38aa3b, v79
	v_fmamk_f32 v102, v102, 0x3e38aa3b, v79
	v_fmamk_f32 v103, v103, 0x3e38aa3b, v79
.Lsel2_A_max:
	v_max3_f32 v105, v100, v101, v102
	v_max_f32_e32 v105, v105, v103
	s_nop 1
	v_max_f32_dpp v105, v105, v105 row_ror:4 row_mask:0xf bank_mask:0xf bound_ctrl:1
	s_nop 1
	v_max_f32_dpp v105, v105, v105 row_ror:8 row_mask:0xf bank_mask:0xf bound_ctrl:1
	s_nop 0
	v_mov_b32_e32 v244, v105
	s_nop 1
	v_permlane16_swap_b32_e32 v105, v244
	s_nop 0
	v_max_f32_e32 v105, v105, v244
	v_mov_b32_e32 v244, v105
	s_nop 1
	v_permlane32_swap_b32_e32 v105, v244
	s_nop 0
	v_max_f32_e32 v105, v105, v244
	v_cmp_gt_f32_e32 vcc, v105, v245
	s_cbranch_vccnz .Lsel2_A_resc
.Lsel2_A_exp:
	v_exp_f32_e32 v100, v100
	v_exp_f32_e32 v101, v101
	v_exp_f32_e32 v102, v102
	v_exp_f32_e32 v103, v103
	s_nop 0
	v_add_f32_e32 v254, v100, v101
	v_add_f32_e32 v255, v102, v103
	v_cvt_pk_fp8_f32 v246, v100, v101
	v_add_f32_e32 v254, v254, v255
	s_nop 0
	v_cvt_pk_fp8_f32 v246, v102, v103 op_sel:[0,0,1]
	v_add_f32_e32 v77, v77, v254
	s_nop 1
	v_mov_b32_dpp v250, v246 row_ror:4 row_mask:0xf bank_mask:0xf bound_ctrl:1
	v_mov_b32_dpp v251, v246 row_ror:12 row_mask:0xf bank_mask:0xf bound_ctrl:1
	v_mov_b32_dpp v248, v246 row_ror:8 row_mask:0xf bank_mask:0xf bound_ctrl:1
	v_cndmask_b32_e64 v247, v251, v250, s[16:17]
	v_cndmask_b32_e64 v249, v250, v251, s[16:17]
	s_add_i32 s5, s48, 1
	s_cmp_lt_i32 s5, s35
	s_cbranch_scc1 .Lsel2_A_w4
	s_waitcnt vmcnt(0)
.Lsel2_A_w4:
	s_waitcnt vmcnt(4)
	s_nop 0
	v_mfma_f32_16x16x32_fp8_fp8 v[32:35], v[52:53], v[246:247], v[32:35]
	v_mfma_f32_16x16x32_fp8_fp8 v[28:31], v[54:55], v[246:247], v[28:31]
	v_mfma_f32_16x16x32_fp8_fp8 v[24:27], v[56:57], v[246:247], v[24:27]
	v_mfma_f32_16x16x32_fp8_fp8 v[20:23], v[58:59], v[246:247], v[20:23]
	v_mfma_f32_16x16x32_fp8_fp8 v[32:35], v[60:61], v[248:249], v[32:35]
	v_mfma_f32_16x16x32_fp8_fp8 v[28:31], v[62:63], v[248:249], v[28:31]
	v_mfma_f32_16x16x32_fp8_fp8 v[24:27], v[64:65], v[248:249], v[24:27]
	v_mfma_f32_16x16x32_fp8_fp8 v[20:23], v[66:67], v[248:249], v[20:23]
	s_cbranch_scc0 .Lsel2_qend
	s_add_u32 s30, s62, s51
	s_addc_u32 s31, s63, 0
	global_load_dwordx4 v[52:55], v252, s[30:31]
	global_load_dwordx4 v[56:59], v252, s[30:31] offset:1024
	global_load_dwordx4 v[60:63], v252, s[30:31] offset:2048
	global_load_dwordx4 v[64:67], v252, s[30:31] offset:3072
	s_mov_b32 s54, s50
	s_mov_b32 s48, s5
	s_branch .Lsel2_B
.Lsel2_A_resc:
	v_max_f32_e32 v254, 0, v105
	v_max_f32_e32 v255, v105, v245
	v_exp_f32_e64 v254, -v254
	v_mov_b32_e32 v245, 0
	v_sub_f32_e32 v78, v78, v255
	v_sub_f32_e32 v100, v100, v255
	v_sub_f32_e32 v101, v101, v255
	v_sub_f32_e32 v102, v102, v255
	v_sub_f32_e32 v103, v103, v255
	v_add_f32_e32 v79, v253, v78
	v_mul_f32_e32 v77, v77, v254
	v_pk_mul_f32 v[20:21], v[20:21], v[254:255] op_sel_hi:[1,0]
	v_pk_mul_f32 v[22:23], v[22:23], v[254:255] op_sel_hi:[1,0]
	v_pk_mul_f32 v[24:25], v[24:25], v[254:255] op_sel_hi:[1,0]
	v_pk_mul_f32 v[26:27], v[26:27], v[254:255] op_sel_hi:[1,0]
	v_pk_mul_f32 v[28:29], v[28:29], v[254:255] op_sel_hi:[1,0]
	v_pk_mul_f32 v[30:31], v[30:31], v[254:255] op_sel_hi:[1,0]
	v_pk_mul_f32 v[32:33], v[32:33], v[254:255] op_sel_hi:[1,0]
	v_pk_mul_f32 v[34:35], v[34:35], v[254:255] op_sel_hi:[1,0]
	s_branch .Lsel2_A_exp
.Lsel2_A_near:
	s_lshl_b32 s4, s54, 6
	v_mov_b32_e32 v255, 0xff800000
	v_subrev_u32_e32 v254, s4, v104
	v_add_u32_e32 v250, -1, v254
	v_add_u32_e32 v251, -2, v254
	v_add_u32_e32 v244, -3, v254
	v_min_u32_e32 v246, 0x7f, v254
	v_min_u32_e32 v247, 0x7f, v250
	v_min_u32_e32 v248, 0x7f, v251
	v_min_u32_e32 v249, 0x7f, v244
	v_lshl_add_u32 v246, v246, 2, v80
	v_lshl_add_u32 v247, v247, 2, v80
	v_lshl_add_u32 v248, v248, 2, v80
	v_lshl_add_u32 v249, v249, 2, v80
	ds_read_b32 v246, v246
	ds_read_b32 v247, v247
	ds_read_b32 v248, v248
	ds_read_b32 v249, v249
	s_waitcnt lgkmcnt(0)
	v_fmamk_f32 v246, v246, 0x3fb8aa3b, v78
	v_fmamk_f32 v247, v247, 0x3fb8aa3b, v78
	v_fmamk_f32 v248, v248, 0x3fb8aa3b, v78
	v_fmamk_f32 v249, v249, 0x3fb8aa3b, v78
	v_fmamk_f32 v100, v100, 0x3e38aa3b, v246
	v_fmamk_f32 v101, v101, 0x3e38aa3b, v247
	v_fmamk_f32 v102, v102, 0x3e38aa3b, v248
	v_fmamk_f32 v103, v103, 0x3e38aa3b, v249
	v_cmp_le_i32_e32 vcc, 0, v254
	s_nop 1
	v_cndmask_b32_e32 v100, v255, v100, vcc
	v_cmp_le_i32_e32 vcc, 0, v250
	s_nop 1
	v_cndmask_b32_e32 v101, v255, v101, vcc
	v_cmp_le_i32_e32 vcc, 0, v251
	s_nop 1
	v_cndmask_b32_e32 v102, v255, v102, vcc
	v_cmp_le_i32_e32 vcc, 0, v244
	s_nop 1
	v_cndmask_b32_e32 v103, v255, v103, vcc
	s_branch .Lsel2_A_max
.Lsel2_B:
	s_waitcnt vmcnt(4)
	v_mfma_f32_16x16x32_fp8_fp8 v[100:103], v[36:37], v[84:85], 0
	v_mfma_f32_16x16x32_fp8_fp8 v[100:103], v[38:39], v[86:87], v[100:103]
	v_mfma_f32_16x16x32_fp8_fp8 v[100:103], v[40:41], v[88:89], v[100:103]
	v_mfma_f32_16x16x32_fp8_fp8 v[100:103], v[42:43], v[90:91], v[100:103]
	v_mfma_f32_16x16x32_fp8_fp8 v[100:103], v[44:45], v[92:93], v[100:103]
	v_mfma_f32_16x16x32_fp8_fp8 v[100:103], v[46:47], v[94:95], v[100:103]
	v_mfma_f32_16x16x32_fp8_fp8 v[100:103], v[48:49], v[96:97], v[100:103]
	v_mfma_f32_16x16x32_fp8_fp8 v[100:103], v[50:51], v[98:99], v[100:103]
	s_add_i32 s5, s48, 1
	s_cmp_lt_i32 s5, s35
	s_cbranch_scc0 .Lsel2_B_nonext
	v_readlane_b32 s50, v76, s5
	s_lshl_b32 s51, s50, 12
	s_add_u32 s30, s46, s51
	s_addc_u32 s31, s47, 0
	global_load_dwordx4 v[2:5], v252, s[30:31]
	global_load_dwordx4 v[6:9], v252, s[30:31] offset:1024
	global_load_dwordx4 v[12:15], v252, s[30:31] offset:2048
	global_load_dwordx4 v[16:19], v252, s[30:31] offset:3072
	s_branch .Lsel2_B_sm

.Lsel2_qend:
	s_nop 1
	v_add_f32_dpp v77, v77, v77 row_ror:4 row_mask:0xf bank_mask:0xf bound_ctrl:1
	s_nop 1
	v_add_f32_dpp v77, v77, v77 row_ror:8 row_mask:0xf bank_mask:0xf bound_ctrl:1
	s_nop 0
	v_mov_b32_e32 v244, v77
	s_nop 1
	v_permlane16_swap_b32_e32 v77, v244
	s_nop 0
	v_add_f32_e32 v77, v77, v244
	v_mov_b32_e32 v244, v77
	s_nop 1
	v_permlane32_swap_b32_e32 v77, v244
	s_nop 0
	v_add_f32_e32 v87, v77, v244
	s_branch .LBB0_1585

.LBB0_2050:
	s_or_b32 s50, s23, s47
	s_ashr_i32 s5, s50, 31
	v_readlane_b32 s30, v243, 32
	v_and_b32_e32 v76, 15, v181
	s_add_u32 s27, s50, s30
	s_addc_u32 s29, s5, 0
	s_mul_i32 s5, s29, 0x1800
	v_mad_u64_u32 v[44:45], s[30:31], s27, v212, v[68:69]
	v_lshl_add_u32 v76, v76, 2, s25
	v_add_u32_e32 v45, s5, v45
	global_load_dwordx4 v[36:39], v[44:45], off
	global_load_dwordx4 v[40:43], v[44:45], off offset:64
	ds_read_b32 v76, v76
	s_lshl_b32 s5, s23, 2
	s_add_i32 s5, s46, s5
	v_mov_b32_e32 v77, s5
	ds_read_b32 v77, v77 offset:17408
	v_lshlrev_b32_e32 v252, 4, v181
	v_readfirstlane_b32 s40, v70
	v_readfirstlane_b32 s41, v71
	v_readfirstlane_b32 s62, v72
	v_readfirstlane_b32 s63, v73
	v_mov_b64_e32 v[20:21], 0
	v_mov_b64_e32 v[22:23], 0
	v_mov_b64_e32 v[24:25], 0
	v_mov_b64_e32 v[26:27], 0
	v_mov_b64_e32 v[28:29], 0
	v_mov_b64_e32 v[30:31], 0
	v_mov_b64_e32 v[32:33], 0
	v_mov_b64_e32 v[34:35], 0
	v_sub_u32_e32 v104, s50, v82
	v_mov_b32_e32 v78, 0
	v_mov_b32_e32 v245, 0xff800000
	s_waitcnt lgkmcnt(0)
	v_mul_f32_e32 v253, 0x3fb8aa3b, v81
	v_readfirstlane_b32 s35, v77
	v_readlane_b32 s38, v76, 0
	v_mov_b32_e32 v77, 0
	v_mov_b32_e32 v79, v253
	s_mov_b32 s48, 0
	s_lshl_b32 s55, s38, 12
	s_add_u32 s30, s40, s55
	s_addc_u32 s31, s41, 0
	global_load_dwordx4 v[2:5], v252, s[30:31]
	global_load_dwordx4 v[6:9], v252, s[30:31] offset:1024
	global_load_dwordx4 v[12:15], v252, s[30:31] offset:2048
	global_load_dwordx4 v[16:19], v252, s[30:31] offset:3072
	s_add_u32 s30, s62, s55
	s_addc_u32 s31, s63, 0
	global_load_dwordx4 v[52:55], v252, s[30:31]
	global_load_dwordx4 v[56:59], v252, s[30:31] offset:1024
	global_load_dwordx4 v[60:63], v252, s[30:31] offset:2048
	global_load_dwordx4 v[64:67], v252, s[30:31] offset:3072
	s_and_b64 s[4:5], s[6:7], s[8:9]
	s_andn2_b64 s[54:55], s[8:9], s[6:7]
	s_andn2_b64 s[70:71], s[6:7], s[8:9]
	s_nor_b64 s[30:31], s[6:7], s[8:9]
	s_waitcnt vmcnt(8)
	v_lshlrev_b32_e32 v254, 16, v36
	v_and_b32_e32 v255, 0xffff0000, v36
	v_mul_f32_e32 v254, 0x41000000, v254
	v_mul_f32_e32 v255, 0x41000000, v255
	v_lshlrev_b32_e32 v250, 16, v37
	v_and_b32_e32 v251, 0xffff0000, v37
	v_cvt_pk_fp8_f32 v100, v254, v255
	v_mul_f32_e32 v250, 0x41000000, v250
	v_mul_f32_e32 v251, 0x41000000, v251
	s_nop 0
	v_cvt_pk_fp8_f32 v100, v250, v251 op_sel:[0,0,1]
	v_lshlrev_b32_e32 v254, 16, v38
	v_and_b32_e32 v255, 0xffff0000, v38
	v_mul_f32_e32 v254, 0x41000000, v254
	v_mul_f32_e32 v255, 0x41000000, v255
	v_lshlrev_b32_e32 v250, 16, v39
	v_and_b32_e32 v251, 0xffff0000, v39
	v_cvt_pk_fp8_f32 v101, v254, v255
	v_mul_f32_e32 v250, 0x41000000, v250
	v_mul_f32_e32 v251, 0x41000000, v251
	s_nop 0
	v_cvt_pk_fp8_f32 v101, v250, v251 op_sel:[0,0,1]
	v_lshlrev_b32_e32 v254, 16, v40
	v_and_b32_e32 v255, 0xffff0000, v40
	v_mul_f32_e32 v254, 0x41000000, v254
	v_mul_f32_e32 v255, 0x41000000, v255
	v_lshlrev_b32_e32 v250, 16, v41
	v_and_b32_e32 v251, 0xffff0000, v41
	v_cvt_pk_fp8_f32 v102, v254, v255
	v_mul_f32_e32 v250, 0x41000000, v250
	v_mul_f32_e32 v251, 0x41000000, v251
	s_nop 0
	v_cvt_pk_fp8_f32 v102, v250, v251 op_sel:[0,0,1]
	v_lshlrev_b32_e32 v254, 16, v42
	v_and_b32_e32 v255, 0xffff0000, v42
	v_mul_f32_e32 v254, 0x41000000, v254
	v_mul_f32_e32 v255, 0x41000000, v255
	v_lshlrev_b32_e32 v250, 16, v43
	v_and_b32_e32 v251, 0xffff0000, v43
	v_cvt_pk_fp8_f32 v103, v254, v255
	v_mul_f32_e32 v250, 0x41000000, v250
	v_mul_f32_e32 v251, 0x41000000, v251
	s_nop 0
	v_cvt_pk_fp8_f32 v103, v250, v251 op_sel:[0,0,1]
	s_nop 1
	v_cndmask_b32_e64 v84, 0, v100, s[4:5]
	v_cndmask_b32_e64 v85, 0, v101, s[4:5]
	v_cndmask_b32_e64 v86, 0, v102, s[4:5]
	v_cndmask_b32_e64 v87, 0, v103, s[4:5]
	v_cndmask_b32_e64 v88, 0, v100, s[54:55]
	v_cndmask_b32_e64 v89, 0, v101, s[54:55]
	v_cndmask_b32_e64 v90, 0, v102, s[54:55]
	v_cndmask_b32_e64 v91, 0, v103, s[54:55]
	v_cndmask_b32_e64 v92, 0, v100, s[70:71]
	v_cndmask_b32_e64 v93, 0, v101, s[70:71]
	v_cndmask_b32_e64 v94, 0, v102, s[70:71]
	v_cndmask_b32_e64 v95, 0, v103, s[70:71]
	v_cndmask_b32_e64 v96, 0, v100, s[30:31]
	v_cndmask_b32_e64 v97, 0, v101, s[30:31]
	v_cndmask_b32_e64 v98, 0, v102, s[30:31]
	v_cndmask_b32_e64 v99, 0, v103, s[30:31]
	s_nop 1
.Lsel3_A:
	s_waitcnt vmcnt(4)
	v_mfma_f32_16x16x32_fp8_fp8 v[100:103], v[2:3], v[84:85], 0
	v_mfma_f32_16x16x32_fp8_fp8 v[100:103], v[4:5], v[86:87], v[100:103]
	v_mfma_f32_16x16x32_fp8_fp8 v[100:103], v[6:7], v[88:89], v[100:103]
	v_mfma_f32_16x16x32_fp8_fp8 v[100:103], v[8:9], v[90:91], v[100:103]
	v_mfma_f32_16x16x32_fp8_fp8 v[100:103], v[12:13], v[92:93], v[100:103]
	v_mfma_f32_16x16x32_fp8_fp8 v[100:103], v[14:15], v[94:95], v[100:103]
	v_mfma_f32_16x16x32_fp8_fp8 v[100:103], v[16:17], v[96:97], v[100:103]
	v_mfma_f32_16x16x32_fp8_fp8 v[100:103], v[18:19], v[98:99], v[100:103]
	s_add_i32 s5, s48, 1
	s_cmp_lt_i32 s5, s35
	s_cbranch_scc0 .Lsel3_A_nonext
	v_readlane_b32 s54, v76, s5
	s_lshl_b32 s55, s54, 12
	s_add_u32 s30, s40, s55
	s_addc_u32 s31, s41, 0
	global_load_dwordx4 v[36:39], v252, s[30:31]
	global_load_dwordx4 v[40:43], v252, s[30:31] offset:1024
	global_load_dwordx4 v[44:47], v252, s[30:31] offset:2048
	global_load_dwordx4 v[48:51], v252, s[30:31] offset:3072
	s_branch .Lsel3_A_sm

.Lsel3_A_sm:
	s_cmp_ge_i32 s38, s21
	s_cbranch_scc1 .Lsel3_A_near
	v_fmamk_f32 v100, v100, 0x3e38aa3b, v79
	v_fmamk_f32 v101, v101, 0x3e38aa3b, v79
	v_fmamk_f32 v102, v102, 0x3e38aa3b, v79
	v_fmamk_f32 v103, v103, 0x3e38aa3b, v79

.Lsel3_A_exp:
	v_exp_f32_e32 v100, v100
	v_exp_f32_e32 v101, v101
	v_exp_f32_e32 v102, v102
	v_exp_f32_e32 v103, v103
	s_nop 0
	v_add_f32_e32 v254, v100, v101
	v_add_f32_e32 v255, v102, v103
	v_cvt_pk_fp8_f32 v246, v100, v101
	v_add_f32_e32 v254, v254, v255
	s_nop 0
	v_cvt_pk_fp8_f32 v246, v102, v103 op_sel:[0,0,1]
	v_add_f32_e32 v77, v77, v254
	s_nop 1
	v_mov_b32_dpp v250, v246 row_ror:4 row_mask:0xf bank_mask:0xf bound_ctrl:1
	v_mov_b32_dpp v251, v246 row_ror:12 row_mask:0xf bank_mask:0xf bound_ctrl:1
	v_mov_b32_dpp v248, v246 row_ror:8 row_mask:0xf bank_mask:0xf bound_ctrl:1
	v_cndmask_b32_e64 v247, v251, v250, s[10:11]
	v_cndmask_b32_e64 v249, v250, v251, s[10:11]
	s_add_i32 s5, s48, 1
	s_cmp_lt_i32 s5, s35
	s_cbranch_scc1 .Lsel3_A_w4
	s_waitcnt vmcnt(0)
.Lsel3_A_w4:
	s_waitcnt vmcnt(4)
	s_nop 0
	v_mfma_f32_16x16x32_fp8_fp8 v[32:35], v[52:53], v[246:247], v[32:35]
	v_mfma_f32_16x16x32_fp8_fp8 v[28:31], v[54:55], v[246:247], v[28:31]
	v_mfma_f32_16x16x32_fp8_fp8 v[24:27], v[56:57], v[246:247], v[24:27]
	v_mfma_f32_16x16x32_fp8_fp8 v[20:23], v[58:59], v[246:247], v[20:23]
	v_mfma_f32_16x16x32_fp8_fp8 v[32:35], v[60:61], v[248:249], v[32:35]
	v_mfma_f32_16x16x32_fp8_fp8 v[28:31], v[62:63], v[248:249], v[28:31]
	v_mfma_f32_16x16x32_fp8_fp8 v[24:27], v[64:65], v[248:249], v[24:27]
	v_mfma_f32_16x16x32_fp8_fp8 v[20:23], v[66:67], v[248:249], v[20:23]
	s_cbranch_scc0 .Lsel3_qend
	s_add_u32 s30, s62, s55
	s_addc_u32 s31, s63, 0
	global_load_dwordx4 v[52:55], v252, s[30:31]
	global_load_dwordx4 v[56:59], v252, s[30:31] offset:1024
	global_load_dwordx4 v[60:63], v252, s[30:31] offset:2048
	global_load_dwordx4 v[64:67], v252, s[30:31] offset:3072
	s_mov_b32 s38, s54
	s_mov_b32 s48, s5
	s_branch .Lsel3_B

.Lsel3_A_near:
	s_lshl_b32 s4, s38, 6
	v_mov_b32_e32 v255, 0xff800000
	v_subrev_u32_e32 v254, s4, v104
	v_add_u32_e32 v250, -1, v254
	v_add_u32_e32 v251, -2, v254
	v_add_u32_e32 v244, -3, v254
	v_min_u32_e32 v246, 0x7f, v254
	v_min_u32_e32 v247, 0x7f, v250
	v_min_u32_e32 v248, 0x7f, v251
	v_min_u32_e32 v249, 0x7f, v244
	v_lshl_add_u32 v246, v246, 2, v80
	v_lshl_add_u32 v247, v247, 2, v80
	v_lshl_add_u32 v248, v248, 2, v80
	v_lshl_add_u32 v249, v249, 2, v80
	ds_read_b32 v246, v246
	ds_read_b32 v247, v247
	ds_read_b32 v248, v248
	ds_read_b32 v249, v249
	s_waitcnt lgkmcnt(0)
	v_fmamk_f32 v246, v246, 0x3fb8aa3b, v78
	v_fmamk_f32 v247, v247, 0x3fb8aa3b, v78
	v_fmamk_f32 v248, v248, 0x3fb8aa3b, v78
	v_fmamk_f32 v249, v249, 0x3fb8aa3b, v78
	v_fmamk_f32 v100, v100, 0x3e38aa3b, v246
	v_fmamk_f32 v101, v101, 0x3e38aa3b, v247
	v_fmamk_f32 v102, v102, 0x3e38aa3b, v248
	v_fmamk_f32 v103, v103, 0x3e38aa3b, v249
	v_cmp_le_i32_e32 vcc, 0, v254
	s_nop 1
	v_cndmask_b32_e32 v100, v255, v100, vcc
	v_cmp_le_i32_e32 vcc, 0, v250
	s_nop 1
	v_cndmask_b32_e32 v101, v255, v101, vcc
	v_cmp_le_i32_e32 vcc, 0, v251
	s_nop 1
	v_cndmask_b32_e32 v102, v255, v102, vcc
	v_cmp_le_i32_e32 vcc, 0, v244
	s_nop 1
	v_cndmask_b32_e32 v103, v255, v103, vcc
	s_branch .Lsel3_A_max
.Lsel3_B:
	s_waitcnt vmcnt(4)
	v_mfma_f32_16x16x32_fp8_fp8 v[100:103], v[36:37], v[84:85], 0
	v_mfma_f32_16x16x32_fp8_fp8 v[100:103], v[38:39], v[86:87], v[100:103]
	v_mfma_f32_16x16x32_fp8_fp8 v[100:103], v[40:41], v[88:89], v[100:103]
	v_mfma_f32_16x16x32_fp8_fp8 v[100:103], v[42:43], v[90:91], v[100:103]
	v_mfma_f32_16x16x32_fp8_fp8 v[100:103], v[44:45], v[92:93], v[100:103]
	v_mfma_f32_16x16x32_fp8_fp8 v[100:103], v[46:47], v[94:95], v[100:103]
	v_mfma_f32_16x16x32_fp8_fp8 v[100:103], v[48:49], v[96:97], v[100:103]
	v_mfma_f32_16x16x32_fp8_fp8 v[100:103], v[50:51], v[98:99], v[100:103]
	s_add_i32 s5, s48, 1
	s_cmp_lt_i32 s5, s35
	s_cbranch_scc0 .Lsel3_B_nonext
	v_readlane_b32 s54, v76, s5
	s_lshl_b32 s55, s54, 12
	s_add_u32 s30, s40, s55
	s_addc_u32 s31, s41, 0
	global_load_dwordx4 v[2:5], v252, s[30:31]
	global_load_dwordx4 v[6:9], v252, s[30:31] offset:1024
	global_load_dwordx4 v[12:15], v252, s[30:31] offset:2048
	global_load_dwordx4 v[16:19], v252, s[30:31] offset:3072
	s_branch .Lsel3_B_sm

	.amdhsa_kernel _Z8mega_fwd6Params
		.amdhsa_group_segment_fixed_size 0
		.amdhsa_private_segment_fixed_size 0
		.amdhsa_kernarg_size 480
		.amdhsa_user_sgpr_count 2
		.amdhsa_user_sgpr_dispatch_ptr 0
		.amdhsa_user_sgpr_queue_ptr 0
		.amdhsa_user_sgpr_kernarg_segment_ptr 1
		.amdhsa_user_sgpr_dispatch_id 0
		.amdhsa_user_sgpr_kernarg_preload_length 0
		.amdhsa_user_sgpr_kernarg_preload_offset 0
		.amdhsa_user_sgpr_private_segment_size 0
		.amdhsa_uses_dynamic_stack 0
		.amdhsa_enable_private_segment 0
		.amdhsa_system_sgpr_workgroup_id_x 1
		.amdhsa_system_sgpr_workgroup_id_y 0
		.amdhsa_system_sgpr_workgroup_id_z 0
		.amdhsa_system_sgpr_workgroup_info 0
		.amdhsa_system_vgpr_workitem_id 2
		.amdhsa_next_free_vgpr 256
		.amdhsa_next_free_sgpr 100
		.amdhsa_accum_offset 256
		.amdhsa_reserve_vcc 1
		.amdhsa_float_round_mode_32 0
		.amdhsa_float_round_mode_16_64 0
		.amdhsa_float_denorm_mode_32 3
		.amdhsa_float_denorm_mode_16_64 3
		.amdhsa_dx10_clamp 1
		.amdhsa_ieee_mode 1
		.amdhsa_fp16_overflow 0
		.amdhsa_tg_split 0
		.amdhsa_exception_fp_ieee_invalid_op 0
		.amdhsa_exception_fp_denorm_src 0
		.amdhsa_exception_fp_ieee_div_zero 0
		.amdhsa_exception_fp_ieee_overflow 0
		.amdhsa_exception_fp_ieee_underflow 0
		.amdhsa_exception_fp_ieee_inexact 0
		.amdhsa_exception_int_div_zero 0
	.end_amdhsa_kernel

amdhsa.kernels:
  - .agpr_count:     0
    .args:
      - .offset:         0
        .size:           224
        .value_kind:     by_value
      - .offset:         224
        .size:           4
        .value_kind:     hidden_block_count_x
      - .offset:         228
        .size:           4
        .value_kind:     hidden_block_count_y
      - .offset:         232
        .size:           4
        .value_kind:     hidden_block_count_z
      - .offset:         236
        .size:           2
        .value_kind:     hidden_group_size_x
      - .offset:         238
        .size:           2
        .value_kind:     hidden_group_size_y
      - .offset:         240
        .size:           2
        .value_kind:     hidden_group_size_z
      - .offset:         242
        .size:           2
        .value_kind:     hidden_remainder_x
      - .offset:         244
        .size:           2
        .value_kind:     hidden_remainder_y
      - .offset:         246
        .size:           2
        .value_kind:     hidden_remainder_z
      - .offset:         264
        .size:           8
        .value_kind:     hidden_global_offset_x
      - .offset:         272
        .size:           8
        .value_kind:     hidden_global_offset_y
      - .offset:         280
        .size:           8
        .value_kind:     hidden_global_offset_z
      - .offset:         288
        .size:           2
        .value_kind:     hidden_grid_dims
      - .offset:         312
        .size:           8
        .value_kind:     hidden_multigrid_sync_arg
      - .offset:         344
        .size:           4
        .value_kind:     hidden_dynamic_lds_size
    .group_segment_fixed_size: 0
    .kernarg_segment_align: 8
    .kernarg_segment_size: 480
    .language:       OpenCL C
    .language_version:
      - 2
      - 0
    .max_flat_workgroup_size: 512
    .name:           _Z8mega_fwd6Params
    .private_segment_fixed_size: 0
    .sgpr_count:     106
    .sgpr_spill_count: 117
    .symbol:         _Z8mega_fwd6Params.kd
    .uniform_work_group_size: 1
    .uses_dynamic_stack: false
    .vgpr_count:     256
    .vgpr_spill_count: 0
    .wavefront_size: 64
